# m4_item: q/k staging loads all in flight (were 4 serialized load-wait-ds_write), 8 per-head LN gain vectors loaded together (were 8 serialized load-wait-store); stacked on v19
# speedup vs baseline: 1.0194x; 1.0009x over previous
; __device__ __forceinline__ float bflo(unsigned w) { return __uint_as_float(w << 16); }
; __device__ __forceinline__ float bfhi(unsigned w) { return __uint_as_float(w & 0xffff0000u); }
; __device__ __forceinline__ unsigned pk2(float lo, float hi) { unsigned r; asm volatile("v_cvt_pk_bf16_f32 %0, %1, %2" : "=v"(r) : "v"(lo), "v"(hi)); return r; }
; __device__ __forceinline__ void m4_item(CArgs& A, Frame& F, int L, int item) {
;     ...
;     const float rstd = 1.0f / sqrtf((red2[l * 2] + red2[l * 2 + 1]) * (1.f / 256.f) + LN_EPS);
;     const float* gain = A.in[11] + (size_t)L * D + h * 256; bf16* ya = WSP(bf16, WS_YA) + (size_t)(tok0 + l) * D + h * 256;
; #pragma unroll
;     for (int nt = 0; nt < 8; ++nt) { const int vc = 128 * vh + 16 * nt + 4 * fq;
;         const f32x4 g = *(const f32x4*)(gain + vc); const u32x2 o = ogv[nt];
;         u32x2 w; w.x = pk2(hv[nt][0] * rstd * g[0] * bflo(o.x), hv[nt][1] * rstd * g[1] * bfhi(o.x)); w.y = pk2(hv[nt][2] * rstd * g[2] * bflo(o.y), hv[nt][3] * rstd * g[3] * bfhi(o.y));
;         *(u32x2*)(ya + vc) = w; }
.LBB0_881:
	s_or_b64 exec, exec, s[10:11]
	v_lshl_add_u64 v[20:21], s[14:15], 0, v[20:21]
	v_lshl_add_u64 v[66:67], v[20:21], 0, s[8:9]
	s_lshl_b32 s8, s86, 2
	v_lshl_add_u64 v[20:21], v[90:91], 0, s[8:9]
	s_waitcnt lgkmcnt(0)
	s_barrier
	global_load_dwordx4 v[62:65], v[20:21], off
	global_load_dwordx4 v[112:115], v[20:21], off offset:64
	global_load_dwordx4 v[116:119], v[20:21], off offset:128
	global_load_dwordx4 v[196:199], v[20:21], off offset:192
	global_load_dwordx4 v[208:211], v[20:21], off offset:256
	global_load_dwordx4 v[212:215], v[20:21], off offset:320
	global_load_dwordx4 v[216:219], v[20:21], off offset:384
	global_load_dwordx4 v[220:223], v[20:21], off offset:448
	ds_read_b64 v[68:69], v174
	s_waitcnt vmcnt(15)
	v_lshlrev_b32_e32 v30, 16, v18
	v_and_b32_e32 v44, 0xffff0000, v18
	v_lshlrev_b32_e32 v46, 16, v19
	v_and_b32_e32 v48, 0xffff0000, v19
	s_waitcnt lgkmcnt(0)
	v_add_f32_e32 v40, v68, v69
	v_fmamk_f32 v40, v40, 0x3b800000, v252
	v_mul_f32_e32 v42, 0x4f800000, v40
	v_cmp_gt_f32_e32 vcc, s31, v40
	v_readlane_b32 s8, v254, 37
	s_add_i32 s0, s0, s94
	v_cndmask_b32_e32 v40, v40, v42, vcc
	v_sqrt_f32_e32 v42, v40
	s_add_i32 s36, s36, s8
	v_readlane_b32 s16, v254, 25
	v_readlane_b32 s17, v254, 26
	v_add_u32_e32 v18, -1, v42
	v_add_u32_e32 v19, 1, v42
	v_fma_f32 v50, -v18, v42, v40
	v_fma_f32 v52, -v19, v42, v40
	v_cmp_ge_f32_e64 s[88:89], 0, v50
	s_add_u32 s1, s1, s16
	s_addc_u32 s37, s37, s17
	v_cndmask_b32_e64 v18, v42, v18, s[88:89]
	v_cmp_lt_f32_e64 s[88:89], 0, v52
	s_cmpk_gt_i32 s0, 0x3ff
	s_nop 0
	v_cndmask_b32_e64 v18, v18, v19, s[88:89]
	v_mul_f32_e32 v19, 0x37800000, v18
	v_cndmask_b32_e32 v18, v18, v19, vcc
	v_cmp_class_f32_e32 vcc, v40, v234
	s_nop 1
	v_cndmask_b32_e32 v40, v18, v40, vcc
	v_div_scale_f32 v42, s[10:11], v40, v40, 1.0
	v_rcp_f32_e32 v50, v42
	v_lshl_add_u64 v[18:19], v[88:89], 1, v[66:67]
	v_div_scale_f32 v52, vcc, 1.0, v40, 1.0
	v_fma_f32 v66, -v42, v50, 1.0
	v_fmac_f32_e32 v50, v66, v50
	v_mul_f32_e32 v66, v52, v50
	v_fma_f32 v67, -v42, v66, v52
	v_fmac_f32_e32 v66, v67, v50
	v_fma_f32 v42, -v42, v66, v52
	v_div_fmas_f32 v42, v42, v50, v66
	v_div_fixup_f32 v40, v42, v40, 1.0
	v_mul_f32_e32 v42, v61, v40
	v_mul_f32_e32 v25, v25, v40
	v_mul_f32_e32 v50, v60, v40
	v_mul_f32_e32 v23, v23, v40
	v_mul_f32_e32 v29, v29, v40
	v_mul_f32_e32 v27, v27, v40
	v_readlane_b32 s10, v254, 35
	v_readlane_b32 s11, v254, 36
	s_waitcnt vmcnt(0)
; __device__ __forceinline__ float bflo(unsigned w) { return __uint_as_float(w << 16); }
; __device__ __forceinline__ float bfhi(unsigned w) { return __uint_as_float(w & 0xffff0000u); }
; __device__ __forceinline__ unsigned pk2(float lo, float hi) { unsigned r; asm volatile("v_cvt_pk_bf16_f32 %0, %1, %2" : "=v"(r) : "v"(lo), "v"(hi)); return r; }
; __device__ __forceinline__ void m4_item(CArgs& A, Frame& F, int L, int item) {
;     ...
;     const float rstd = 1.0f / sqrtf((red2[l * 2] + red2[l * 2 + 1]) * (1.f / 256.f) + LN_EPS);
;     const float* gain = A.in[11] + (size_t)L * D + h * 256; bf16* ya = WSP(bf16, WS_YA) + (size_t)(tok0 + l) * D + h * 256;
; #pragma unroll
;     for (int nt = 0; nt < 8; ++nt) { const int vc = 128 * vh + 16 * nt + 4 * fq;
;         const f32x4 g = *(const f32x4*)(gain + vc); const u32x2 o = ogv[nt];
;         u32x2 w; w.x = pk2(hv[nt][0] * rstd * g[0] * bflo(o.x), hv[nt][1] * rstd * g[1] * bfhi(o.x)); w.y = pk2(hv[nt][2] * rstd * g[2] * bflo(o.y), hv[nt][3] * rstd * g[3] * bfhi(o.y));
;         *(u32x2*)(ya + vc) = w; }
;     __syncthreads();
	v_mul_f32_e32 v42, v62, v42
	v_mul_f32_e32 v25, v63, v25
	v_mul_f32_e32 v50, v64, v50
	v_mul_f32_e32 v23, v65, v23
	v_mul_f32_e32 v30, v42, v30
	v_mul_f32_e32 v25, v25, v44
	v_mul_f32_e32 v42, v50, v46
	v_mul_f32_e32 v23, v23, v48
	v_cvt_pk_bf16_f32 v60, v30, v25
	v_cvt_pk_bf16_f32 v61, v42, v23
	global_store_dwordx2 v[18:19], v[60:61], off
	v_mov_b64_e32 v[60:61], v[112:113]
	v_mov_b64_e32 v[62:63], v[114:115]
	v_lshlrev_b32_e32 v23, 16, v16
	v_and_b32_e32 v16, 0xffff0000, v16
	v_lshlrev_b32_e32 v25, 16, v17
	v_and_b32_e32 v17, 0xffff0000, v17
	v_mul_f32_e32 v30, v59, v40
	v_mul_f32_e32 v42, v58, v40
	v_lshl_add_u64 v[92:93], v[92:93], 0, s[10:11]
	v_readlane_b32 s10, v254, 23
	v_readlane_b32 s11, v254, 24
	s_nop 0
	v_mul_f32_e32 v29, v61, v29
	v_mul_f32_e32 v27, v63, v27
	v_mul_f32_e32 v30, v60, v30
	v_mul_f32_e32 v42, v62, v42
	v_mul_f32_e32 v16, v29, v16
	v_mul_f32_e32 v17, v27, v17
	v_mul_f32_e32 v23, v30, v23
	v_mul_f32_e32 v25, v42, v25
	v_cvt_pk_bf16_f32 v16, v23, v16
	v_cvt_pk_bf16_f32 v17, v25, v17
	global_store_dwordx2 v[18:19], v[16:17], off offset:32
	v_mov_b64_e32 v[58:59], v[116:117]
	v_mov_b64_e32 v[60:61], v[118:119]
	v_mul_f32_e32 v25, v35, v40
	v_mul_f32_e32 v29, v33, v40
	v_lshlrev_b32_e32 v16, 16, v14
	v_and_b32_e32 v14, 0xffff0000, v14
	v_lshlrev_b32_e32 v17, 16, v15
	v_and_b32_e32 v15, 0xffff0000, v15
	v_mul_f32_e32 v23, v57, v40
	v_mul_f32_e32 v27, v56, v40
	v_mul_f32_e32 v33, v37, v40
	v_mul_f32_e32 v30, v54, v40
	v_lshl_add_u64 v[94:95], v[94:95], 0, s[10:11]
	v_lshl_add_u64 v[96:97], v[96:97], 0, s[10:11]
	v_lshl_add_u64 v[98:99], v[98:99], 0, s[10:11]
	v_lshl_add_u64 v[100:101], v[100:101], 0, s[10:11]
	v_lshl_add_u64 v[102:103], v[102:103], 0, s[10:11]
	v_lshl_add_u64 v[104:105], v[104:105], 0, s[10:11]
	v_lshl_add_u64 v[106:107], v[106:107], 0, s[10:11]
	v_lshl_add_u64 v[108:109], v[108:109], 0, s[10:11]
	s_nop 0
	v_mul_f32_e32 v25, v25, v59
	v_mul_f32_e32 v29, v29, v61
	v_mul_f32_e32 v23, v23, v58
	v_mul_f32_e32 v27, v27, v60
	v_mul_f32_e32 v14, v25, v14
	v_mul_f32_e32 v15, v29, v15
	v_mul_f32_e32 v16, v23, v16
	v_mul_f32_e32 v17, v27, v17
	v_cvt_pk_bf16_f32 v14, v16, v14
	v_cvt_pk_bf16_f32 v15, v17, v15
	global_store_dwordx2 v[18:19], v[14:15], off offset:64
	v_mov_b64_e32 v[14:15], v[196:197]
	v_mov_b64_e32 v[16:17], v[198:199]
	v_mul_f32_e32 v29, v39, v40
	v_lshlrev_b32_e32 v23, 16, v12
	v_and_b32_e32 v12, 0xffff0000, v12
	v_lshlrev_b32_e32 v25, 16, v13
	v_and_b32_e32 v13, 0xffff0000, v13
	v_mul_f32_e32 v27, v55, v40
	s_nop 0
	v_mul_f32_e32 v15, v29, v15
	v_mul_f32_e32 v17, v33, v17
	v_mul_f32_e32 v14, v27, v14
	v_mul_f32_e32 v16, v30, v16
	v_mul_f32_e32 v12, v15, v12
	v_mul_f32_e32 v13, v17, v13
	v_mul_f32_e32 v14, v14, v23
	v_mul_f32_e32 v15, v16, v25
	v_cvt_pk_bf16_f32 v12, v14, v12
	v_cvt_pk_bf16_f32 v13, v15, v13
	global_store_dwordx2 v[18:19], v[12:13], off offset:96
	v_mov_b64_e32 v[12:13], v[208:209]
	v_mov_b64_e32 v[14:15], v[210:211]
	v_mul_f32_e32 v25, v43, v40
	v_mul_f32_e32 v29, v41, v40
	v_lshlrev_b32_e32 v16, 16, v10
	v_and_b32_e32 v10, 0xffff0000, v10
	v_lshlrev_b32_e32 v17, 16, v11
	v_and_b32_e32 v11, 0xffff0000, v11
	v_mul_f32_e32 v23, v38, v40
	v_mul_f32_e32 v27, v36, v40
	s_nop 0
	v_mul_f32_e32 v13, v25, v13
	v_mul_f32_e32 v15, v29, v15
	v_mul_f32_e32 v12, v23, v12
	v_mul_f32_e32 v14, v27, v14
	v_mul_f32_e32 v10, v13, v10
	v_mul_f32_e32 v11, v15, v11
	v_mul_f32_e32 v12, v12, v16
	v_mul_f32_e32 v13, v14, v17
	v_cvt_pk_bf16_f32 v10, v12, v10
	v_cvt_pk_bf16_f32 v11, v13, v11
	global_store_dwordx2 v[18:19], v[10:11], off offset:128
	v_mov_b64_e32 v[10:11], v[212:213]
	v_mov_b64_e32 v[12:13], v[214:215]
	v_mul_f32_e32 v17, v47, v40
	v_mul_f32_e32 v25, v45, v40
	v_lshlrev_b32_e32 v14, 16, v8
	v_and_b32_e32 v8, 0xffff0000, v8
	v_lshlrev_b32_e32 v15, 16, v9
	v_and_b32_e32 v9, 0xffff0000, v9
	v_mul_f32_e32 v16, v34, v40
	v_mul_f32_e32 v23, v32, v40
	s_nop 0
	v_mul_f32_e32 v11, v17, v11
	v_mul_f32_e32 v13, v25, v13
	v_mul_f32_e32 v10, v16, v10
	v_mul_f32_e32 v12, v23, v12
	v_mul_f32_e32 v8, v11, v8
	v_mul_f32_e32 v9, v13, v9
	v_mul_f32_e32 v10, v10, v14
	v_mul_f32_e32 v11, v12, v15
	v_cvt_pk_bf16_f32 v8, v10, v8
	v_cvt_pk_bf16_f32 v9, v11, v9
	global_store_dwordx2 v[18:19], v[8:9], off offset:160
	v_mov_b64_e32 v[8:9], v[216:217]
	v_mov_b64_e32 v[10:11], v[218:219]
	v_mul_f32_e32 v15, v51, v40
	v_mul_f32_e32 v17, v49, v40
	v_lshlrev_b32_e32 v12, 16, v6
	v_and_b32_e32 v6, 0xffff0000, v6
	v_lshlrev_b32_e32 v13, 16, v7
	v_and_b32_e32 v7, 0xffff0000, v7
	v_mul_f32_e32 v14, v28, v40
	v_mul_f32_e32 v16, v26, v40
	s_nop 0
	v_mul_f32_e32 v9, v15, v9
	v_mul_f32_e32 v11, v17, v11
	v_mul_f32_e32 v8, v14, v8
	v_mul_f32_e32 v10, v16, v10
	v_mul_f32_e32 v6, v9, v6
	v_mul_f32_e32 v7, v11, v7
	v_mul_f32_e32 v8, v8, v12
	v_mul_f32_e32 v9, v10, v13
	v_cvt_pk_bf16_f32 v6, v8, v6
	v_cvt_pk_bf16_f32 v7, v9, v7
	global_store_dwordx2 v[18:19], v[6:7], off offset:192
	v_mov_b64_e32 v[6:7], v[220:221]
	v_mov_b64_e32 v[8:9], v[222:223]
	v_mul_f32_e32 v13, v31, v40
	v_mul_f32_e32 v15, v53, v40
	v_lshlrev_b32_e32 v10, 16, v4
	v_and_b32_e32 v4, 0xffff0000, v4
	v_lshlrev_b32_e32 v11, 16, v5
	v_and_b32_e32 v5, 0xffff0000, v5
	v_mul_f32_e32 v12, v24, v40
	v_mul_f32_e32 v14, v22, v40
	s_nop 0
	v_mul_f32_e32 v7, v13, v7
	v_mul_f32_e32 v9, v15, v9
	v_mul_f32_e32 v6, v12, v6
	v_mul_f32_e32 v8, v14, v8
	v_mul_f32_e32 v4, v7, v4
	v_mul_f32_e32 v5, v9, v5
	v_mul_f32_e32 v6, v6, v10
	v_mul_f32_e32 v7, v8, v11
	v_cvt_pk_bf16_f32 v4, v6, v4
	v_cvt_pk_bf16_f32 v5, v7, v5
	global_store_dwordx2 v[18:19], v[4:5], off offset:224
	s_barrier
	s_cbranch_scc1 .LBB0_928

; #define LAS __attribute__((address_space(3)))
; __device__ __forceinline__ void m4_item(CArgs& A, Frame& F, int L, int item) {
;     ...
;     for (int i = 0; i < 2; ++i) { const int idx = F.tid + NT * i, tok = idx >> 4, d8 = idx & 15;
;         *(LAS u32x4*)(qs + tok * 136 + d8 * 8) = *(const u32x4*)(Qm + (size_t)(tok0 + tok) * 512 + h * 128 + d8 * 8);
;         *(LAS u32x4*)(ks_ + tok * 136 + d8 * 8) = *(const u32x4*)(Km + (size_t)(tok0 + tok) * 512 + h * 128 + d8 * 8); }
;     u32x4 rv[4], rc[8];
; #pragma unroll
;     for (int i = 0; i < 4; ++i) { const int idx = F.tid + NT * i, tok = idx >> 5, v8 = idx & 31; rv[i] = *(const u32x4*)(Vm + (size_t)(tok0 + tok) * 1024 + h * 256 + v8 * 8); }
;     if (c > 0) {
;         const bf16* Cc = WSP(bf16, WS_CC) + (size_t)item * 32768;
; #pragma unroll
;         for (int i = 0; i < 8; ++i) { const int idx = F.tid + NT * i, vc = idx >> 4, d8 = idx & 15; rc[i] = *(const u32x4*)(Cc + vc * 128 + d8 * 8); }
;         if (F.tid < 128) sn[F.tid] = WSP(float, WS_NC)[(size_t)item * 128 + F.tid];
.LBB0_884:
	s_lshl_b32 s86, s11, 8
	v_add_u32_e32 v4, s87, v130
	s_add_u32 s16, s28, s86
	v_ashrrev_i32_e32 v5, 31, v4
	s_addc_u32 s17, s29, 0
	v_lshlrev_b64 v[8:9], 10, v[4:5]
	v_lshl_add_u64 v[4:5], s[16:17], 0, v[8:9]
	v_mov_b32_e32 v111, v2
	v_lshl_add_u64 v[4:5], v[4:5], 0, v[110:111]
	global_load_dwordx4 v[4:7], v[4:5], off
	s_add_u32 s18, s34, s86
	v_add_u32_e32 v12, s87, v136
	s_addc_u32 s19, s35, 0
	s_lshl_b32 s8, s11, 9
	v_ashrrev_i32_e32 v13, 31, v12
	v_lshl_add_u64 v[16:17], v[0:1], 0, s[8:9]
	v_lshlrev_b64 v[12:13], 11, v[12:13]
	v_lshl_add_u64 v[12:13], v[16:17], 0, v[12:13]
	global_load_dwordx4 v[12:15], v[12:13], off
	v_add_u32_e32 v18, s87, v137
	v_ashrrev_i32_e32 v19, 31, v18
	v_lshlrev_b64 v[18:19], 11, v[18:19]
	v_lshl_add_u64 v[112:113], s[18:19], 0, v[8:9]
	v_lshl_add_u64 v[112:113], v[112:113], 0, v[110:111]
	global_load_dwordx4 v[112:115], v[112:113], off
	v_add_u32_e32 v116, s87, v132
	v_ashrrev_i32_e32 v117, 31, v116
	v_lshlrev_b64 v[8:9], 10, v[116:117]
	v_lshl_add_u64 v[116:117], s[16:17], 0, v[8:9]
	v_lshl_add_u64 v[116:117], v[116:117], 0, v[110:111]
	global_load_dwordx4 v[116:119], v[116:117], off
	v_lshl_add_u64 v[196:197], s[18:19], 0, v[8:9]
	v_lshl_add_u64 v[196:197], v[196:197], 0, v[110:111]
	global_load_dwordx4 v[196:199], v[196:197], off
	v_add_u32_e32 v8, s87, v135
	v_ashrrev_i32_e32 v9, 31, v8
	v_lshlrev_b64 v[8:9], 11, v[8:9]
	v_lshl_add_u64 v[8:9], v[16:17], 0, v[8:9]
	global_load_dwordx4 v[8:11], v[8:9], off
	s_cmp_eq_u32 s10, 0
	s_waitcnt vmcnt(5)
	ds_write_b128 v131, v[4:7]
	v_add_u32_e32 v4, s87, v134
	v_ashrrev_i32_e32 v5, 31, v4
	v_lshlrev_b64 v[4:5], 11, v[4:5]
	v_lshl_add_u64 v[4:5], v[16:17], 0, v[4:5]
	v_lshl_add_u64 v[16:17], v[16:17], 0, v[18:19]
	global_load_dwordx4 v[4:7], v[4:5], off
	s_nop 0
	global_load_dwordx4 v[16:19], v[16:17], off
	s_waitcnt vmcnt(5)
	ds_write_b128 v131, v[112:115] offset:17408
	s_waitcnt vmcnt(4)
	ds_write_b128 v133, v[116:119]
	s_waitcnt vmcnt(3)
	ds_write_b128 v133, v[196:199] offset:17408
	s_cbranch_scc1 .LBB0_927
	v_lshl_add_u64 v[20:21], s[2:3], 0, v[94:95]
	v_lshl_add_u64 v[22:23], s[2:3], 0, v[96:97]
	global_load_dwordx4 v[80:83], v[20:21], off
	global_load_dwordx4 v[76:79], v[22:23], off
	v_lshl_add_u64 v[20:21], s[2:3], 0, v[98:99]
	v_lshl_add_u64 v[22:23], s[2:3], 0, v[100:101]
	global_load_dwordx4 v[72:75], v[20:21], off
	global_load_dwordx4 v[68:71], v[22:23], off
	v_lshl_add_u64 v[20:21], s[2:3], 0, v[102:103]
	v_lshl_add_u64 v[22:23], s[2:3], 0, v[104:105]
	global_load_dwordx4 v[64:67], v[20:21], off
	global_load_dwordx4 v[60:63], v[22:23], off
	v_lshl_add_u64 v[20:21], s[2:3], 0, v[106:107]
	v_lshl_add_u64 v[22:23], s[2:3], 0, v[108:109]
	global_load_dwordx4 v[56:59], v[20:21], off
	global_load_dwordx4 v[52:55], v[22:23], off
	s_mov_b64 s[16:17], 0
	s_mov_b64 s[10:11], 0
	s_and_saveexec_b64 s[18:19], s[50:51]
	s_cbranch_execz .LBB0_887
	v_lshl_add_u64 v[20:21], s[2:3], 0, v[92:93]
	global_load_dword v111, v[20:21], off
	s_mov_b64 s[10:11], exec
